# speedup vs baseline: 1.0161x; 1.0161x over previous
; #define SBAR() __builtin_amdgcn_sched_barrier(0)
; __device__ __forceinline__ int opq(int x) { asm volatile("" : "+v"(x)); return x; }
; __device__ __forceinline__ int v_st(int k, int c) { const int kk = (k & ~0xC) | ((k & 4) << 1) | ((k & 8) >> 1); return ((kk >> 3) * 4 + (c >> 5)) * 512 + ((kk & 7) * 32 + (c & 31)) * 2; }
; __device__ __forceinline__ int v_rd_base(int lane) { return ((lane & 3) << 3) | (((lane >> 2) & 3) << 6) | (((lane >> 4) & 1) << 5) | (((lane >> 5) & 1) << 8); }
; __device__ __forceinline__ void qkt(f32x16& p0, f32x16& p1, const char* Ks, const bf16x8* qr, int r32, int hi, const f32x16& negm) {
;     ...
;   for (int d0 = 0; d0 < 4; ++d0) { const int cb = (d0 * 16 + hi * 8) * 2;
;     ka[d0] = *reinterpret_cast<const bf16x8*>(Ks + KSWZ(r32, cb)); }
; __device__ __forceinline__ void attn_stream(const u16* __restrict__ Qb, const u16* __restrict__ Kh, const u16* __restrict__ Vh,
;                                             int seq, char* lds, f32x16 (&o)[4]) {
;     ...
;   const int tid = opq((int)threadIdx.x), wid = tid >> 6, lane = tid & 63, r32 = lane & 31, hi = lane >> 5;
;   char* V_lds = lds; char* K_lds = lds + 3 * SHM_V;
;   float* wsl = (float*)(lds + 3 * SHM_V + 3 * SHM_K) + wid * 64; float* li_l = wsl; float* al_l = wsl + 32;
;   float m_reg = 0.f, l_reg = 0.f; bf16x8 qr[4]; f32x16 negm = {};
; #pragma unroll
;   for (int d = 0; d < 4; ++d) o[d] = f32x16{};
;   const u16* Qw = Qb + (size_t)(wid * 32 + r32) * LDQ + hi * 8;
; #pragma unroll
;   for (int d0 = 0; d0 < 4; ++d0) qr[d0] = *reinterpret_cast<const bf16x8*>(Qw + d0 * 16);
;   const int sr = tid >> 4, sc = (tid & 15) * 8, vst0 = v_st(sr, sc), vst1 = v_st(32 + sr, sc);
;   const int kr = tid >> 3, kc = (tid & 7) * 8, kst = KSWZ(kr, kc * 2);
;   const int vb0 = (int)(uintptr_t)(__attribute__((address_space(3))) char*)V_lds + v_rd_base(lane);
;   bf16x8 vsA0, vsA1, ksA, vsB0, vsB1, ksB;
;     ...
;   f32x16 p0, p1; float al; bf16x8 pa0, pa1, pa2, pa3; const int NT = seq / 64;
;     ...
;   const bool late = wid >= 4;
;   __syncthreads();
;   SLOAD(A, 0); SLOAD(B, 64); asm volatile("s_waitcnt vmcnt(0)" ::: "memory"); SWRITE(0, A); SWRITE(1, B);
;   SLOAD(A, 128); SLOAD(B, 192);
;   __syncthreads();
;   qkt(p0, p1, K_lds, qr, r32, hi, negm); SOFTMAX(true); SBAR();
;   if (late) __syncthreads();
;   int t3 = 0;
.LBB0_330:
	s_or_b64 exec, exec, s[4:5]
	v_lshlrev_b32_e32 v19, 4, v43
	v_lshlrev_b32_e32 v18, 3, v43
	v_and_b32_e32 v19, 0xc0, v19
	v_lshlrev_b32_e32 v20, 1, v43
	v_and_or_b32 v19, v18, 24, v19
	v_and_b32_e32 v20, 32, v20
	v_and_b32_e32 v18, 0x100, v18
	v_or3_b32 v18, v19, v20, v18
	v_and_b32_e32 v20, 15, v40
	v_add_u32_e32 v213, 0, v18
	v_mad_i64_i32 v[18:19], s[42:43], s6, v202, v[34:35]
	v_lshlrev_b32_e32 v20, 4, v20
	v_mov_b32_e32 v21, v191
	v_lshl_add_u64 v[18:19], v[18:19], 0, v[20:21]
	v_and_b32_e32 v20, 7, v40
	s_lshl_b32 s5, s3, 1
	s_mul_hi_i32 s57, s6, 0x880000
	s_mul_i32 s56, s6, 0x880000
	v_lshl_add_u64 v[194:195], s[26:27], 0, v[18:19]
	v_mad_i64_i32 v[18:19], s[6:7], s6, v202, v[36:37]
	v_lshlrev_b32_e32 v20, 4, v20
	s_and_b32 s4, s20, 0x100
	s_and_b32 s5, s5, 0x600
	v_lshl_add_u64 v[18:19], v[18:19], 0, v[20:21]
	s_or_b32 s20, s5, s4
	v_cmp_gt_u32_e64 s[4:5], 32, v43
	v_lshl_add_u32 v212, v41, 2, v204
	v_lshl_add_u64 v[196:197], s[26:27], 0, v[18:19]
	v_mov_b64_e32 v[64:65], v[16:17]
	v_mov_b64_e32 v[48:49], v[16:17]
	v_mov_b64_e32 v[32:33], v[16:17]
	s_mov_b32 s21, s40
	s_mov_b32 s41, 0
	v_mov_b64_e32 v[62:63], v[14:15]
	v_mov_b64_e32 v[60:61], v[12:13]
	v_mov_b64_e32 v[58:59], v[10:11]
	v_mov_b64_e32 v[56:57], v[8:9]
	v_mov_b64_e32 v[54:55], v[6:7]
	v_mov_b64_e32 v[52:53], v[4:5]
	v_mov_b64_e32 v[50:51], v[2:3]
	v_mov_b64_e32 v[46:47], v[14:15]
	v_mov_b64_e32 v[44:45], v[12:13]
	v_mov_b64_e32 v[42:43], v[10:11]
	v_mov_b64_e32 v[40:41], v[8:9]
	v_mov_b64_e32 v[38:39], v[6:7]
	v_mov_b64_e32 v[36:37], v[4:5]
	v_mov_b64_e32 v[34:35], v[2:3]
	v_mov_b64_e32 v[30:31], v[14:15]
	v_mov_b64_e32 v[28:29], v[12:13]
	v_mov_b64_e32 v[26:27], v[10:11]
	v_mov_b64_e32 v[24:25], v[8:9]
	v_mov_b64_e32 v[22:23], v[6:7]
	v_mov_b64_e32 v[20:21], v[4:5]
	v_mov_b64_e32 v[18:19], v[2:3]
	s_mov_b32 s48, 0
	v_mov_b32_e32 v67, v66
	v_mov_b32_e32 v68, v66
	v_mov_b32_e32 v69, v66
	v_mov_b32_e32 v70, v66
	v_mov_b32_e32 v71, v66
	v_mov_b32_e32 v72, v66
	v_mov_b32_e32 v73, v66
	v_mov_b32_e32 v74, v66
	v_mov_b32_e32 v75, v66
	v_mov_b32_e32 v76, v66
	v_mov_b32_e32 v77, v66
	v_mov_b32_e32 v78, v66
	v_mov_b32_e32 v79, v66
	v_mov_b32_e32 v80, v66
	v_mov_b32_e32 v81, v66
	s_mov_b32 s99, 1
	s_lshl_b32 s98, s99, 13
	v_add_u32_e32 v252, s98, v208
	v_add_u32_e32 v253, s98, v209
	v_add_u32_e32 v254, s98, v210
	v_add_u32_e32 v255, s98, v211
	ds_read_b128 v[236:239], v252 offset:49152
	ds_read_b128 v[240:243], v253 offset:49152
	ds_read_b128 v[244:247], v254 offset:49152
	ds_read_b128 v[248:251], v255 offset:49152

; #define SBAR() __builtin_amdgcn_sched_barrier(0)
; __device__ __forceinline__ void qkt(f32x16& p0, f32x16& p1, const char* Ks, const bf16x8* qr, int r32, int hi, const f32x16& negm) {
;   bf16x8 ka[4], kb[4];
; #pragma unroll
;   for (int d0 = 0; d0 < 4; ++d0) { const int cb = (d0 * 16 + hi * 8) * 2;
;     ka[d0] = *reinterpret_cast<const bf16x8*>(Ks + KSWZ(r32, cb)); }
; #pragma unroll
;   for (int d0 = 0; d0 < 4; ++d0) { const int cb = (d0 * 16 + hi * 8) * 2;
;     kb[d0] = *reinterpret_cast<const bf16x8*>(Ks + KSWZ(32 + r32, cb)); }
;   asm volatile("s_waitcnt lgkmcnt(0)" ::: "memory");
; #pragma unroll
;   for (int d0 = 0; d0 < 4; ++d0) { asm volatile("" : "+v"(ka[d0])); asm volatile("" : "+v"(kb[d0])); }
;   SBAR();
;   p0 = __builtin_amdgcn_mfma_f32_32x32x16_bf16(ka[0], qr[0], negm, 0, 0, 0);
;   p0 = __builtin_amdgcn_mfma_f32_32x32x16_bf16(ka[1], qr[1], p0, 0, 0, 0);
;   p0 = __builtin_amdgcn_mfma_f32_32x32x16_bf16(ka[2], qr[2], p0, 0, 0, 0);
;   p0 = __builtin_amdgcn_mfma_f32_32x32x16_bf16(ka[3], qr[3], p0, 0, 0, 0);
;   p1 = __builtin_amdgcn_mfma_f32_32x32x16_bf16(kb[0], qr[0], negm, 0, 0, 0);
;   p1 = __builtin_amdgcn_mfma_f32_32x32x16_bf16(kb[1], qr[1], p1, 0, 0, 0);
;   p1 = __builtin_amdgcn_mfma_f32_32x32x16_bf16(kb[2], qr[2], p1, 0, 0, 0);
;   p1 = __builtin_amdgcn_mfma_f32_32x32x16_bf16(kb[3], qr[3], p1, 0, 0, 0);
;   SBAR();
; }
; __device__ __forceinline__ int v_st(int k, int c) { const int kk = (k & ~0xC) | ((k & 4) << 1) | ((k & 8) >> 1); return ((kk >> 3) * 4 + (c >> 5)) * 512 + ((kk & 7) * 32 + (c & 31)) * 2; }
; __device__ __forceinline__ int v_rd_base(int lane) { return ((lane & 3) << 3) | (((lane >> 2) & 3) << 6) | (((lane >> 4) & 1) << 5) | (((lane >> 5) & 1) << 8); }
; template <int OFF> __device__ __forceinline__ s16x4 tr_read(int vb) {
;   s16x4 r; asm volatile("ds_read_b64_tr_b16 %0, %1 offset:%2" : "=&v"(r) : "v"(vb), "i"(OFF) : "memory"); return r;
; }
; template <int D0> __device__ __forceinline__ void pv_rd(s16x4 (&v)[8], int vb) {
;   v[0] = tr_read<v_rd_off(D0, 0, 0)>(vb); v[1] = tr_read<v_rd_off(D0, 0, 1)>(vb); v[2] = tr_read<v_rd_off(D0, 1, 0)>(vb); v[3] = tr_read<v_rd_off(D0, 1, 1)>(vb);
;   v[4] = tr_read<v_rd_off(D0, 2, 0)>(vb); v[5] = tr_read<v_rd_off(D0, 2, 1)>(vb); v[6] = tr_read<v_rd_off(D0, 3, 0)>(vb); v[7] = tr_read<v_rd_off(D0, 3, 1)>(vb);
; }
.LBB0_333:
	s_lshl_b32 s6, s47, 13
	s_add_i32 s6, s6, 0
	v_add_u32_e32 v82, s6, v208
	v_add_u32_e32 v83, s6, v209
	v_add_u32_e32 v84, s6, v210
	v_add_u32_e32 v85, s6, v211
	s_lshl_b32 s49, s48, 14
	v_add_u32_e32 v226, s49, v213
	ds_read_b128 v[218:221], v82 offset:53248
	ds_read_b128 v[222:225], v83 offset:53248
	ds_read_b128 v[198:201], v84 offset:53248
	ds_read_b128 v[214:217], v85 offset:53248
	ds_read_b64_tr_b16 v[98:99], v226 offset:0
	ds_read_b64_tr_b16 v[100:101], v226 offset:0x800
	ds_read_b64_tr_b16 v[102:103], v226 offset:0x1000
	ds_read_b64_tr_b16 v[104:105], v226 offset:0x1800
	ds_read_b64_tr_b16 v[106:107], v226 offset:0x2000
	ds_read_b64_tr_b16 v[108:109], v226 offset:0x2800
	ds_read_b64_tr_b16 v[110:111], v226 offset:0x3000
	ds_read_b64_tr_b16 v[112:113], v226 offset:0x3800
	s_waitcnt lgkmcnt(12)
	v_mfma_f32_32x32x16_bf16 v[82:97], v[236:239], v[130:133], v[66:81]
	v_mfma_f32_32x32x16_bf16 v[82:97], v[240:243], v[134:137], v[82:97]
	v_mfma_f32_32x32x16_bf16 v[82:97], v[244:247], v[138:141], v[82:97]
	v_mfma_f32_32x32x16_bf16 v[82:97], v[248:251], v[142:145], v[82:97]
	s_waitcnt lgkmcnt(8)
	s_and_b64 vcc, exec, s[42:43]
	s_cbranch_vccnz .Lattn_evw_1
	s_lshl_b32 s98, s46, 14
	s_waitcnt vmcnt(3)
	v_add_u32_e32 v252, s98, v205
	v_lshl_add_u32 v254, s46, 13, v207
	v_add_u32_e32 v253, s98, v206
	ds_write_b128 v252, v[146:149]
	ds_write_b128 v253, v[150:153]
	ds_write_b128 v254, v[158:161] offset:49152
.Lattn_evw_1:
	v_mfma_f32_32x32x16_bf16 v[114:129], v[218:221], v[130:133], v[66:81]
	v_mfma_f32_32x32x16_bf16 v[114:129], v[222:225], v[134:137], v[114:129]
	v_mfma_f32_32x32x16_bf16 v[114:129], v[198:201], v[138:141], v[114:129]
	v_mfma_f32_32x32x16_bf16 v[114:129], v[214:217], v[142:145], v[114:129]
	ds_read_b64_tr_b16 v[198:199], v226 offset:0x200
	ds_read_b64_tr_b16 v[200:201], v226 offset:0xa00
	ds_read_b64_tr_b16 v[214:215], v226 offset:0x1200
	ds_read_b64_tr_b16 v[216:217], v226 offset:0x1a00
	ds_read_b64_tr_b16 v[218:219], v226 offset:0x2200
	ds_read_b64_tr_b16 v[220:221], v226 offset:0x2a00
	ds_read_b64_tr_b16 v[222:223], v226 offset:0x3200
	ds_read_b64_tr_b16 v[224:225], v226 offset:0x3a00
	s_waitcnt lgkmcnt(8)
	s_nop 0
	v_mfma_f32_32x32x16_bf16 v[2:17], v[170:173], v[98:101], v[2:17]
	v_mfma_f32_32x32x16_bf16 v[2:17], v[174:177], v[102:105], v[2:17]
	v_mfma_f32_32x32x16_bf16 v[2:17], v[178:181], v[106:109], v[2:17]
	v_mfma_f32_32x32x16_bf16 v[2:17], v[182:185], v[110:113], v[2:17]
	ds_read_b64_tr_b16 v[98:99], v226 offset:0x400
	ds_read_b64_tr_b16 v[100:101], v226 offset:0xc00
	ds_read_b64_tr_b16 v[102:103], v226 offset:0x1400
	ds_read_b64_tr_b16 v[104:105], v226 offset:0x1c00
	ds_read_b64_tr_b16 v[106:107], v226 offset:0x2400
	ds_read_b64_tr_b16 v[108:109], v226 offset:0x2c00
	ds_read_b64_tr_b16 v[110:111], v226 offset:0x3400
	ds_read_b64_tr_b16 v[112:113], v226 offset:0x3c00
	s_waitcnt lgkmcnt(8)
	v_mfma_f32_32x32x16_bf16 v[50:65], v[170:173], v[198:201], v[50:65]
	v_mfma_f32_32x32x16_bf16 v[50:65], v[174:177], v[214:217], v[50:65]
	v_mfma_f32_32x32x16_bf16 v[50:65], v[178:181], v[218:221], v[50:65]
	v_mfma_f32_32x32x16_bf16 v[50:65], v[182:185], v[222:225], v[50:65]
	ds_read_b64_tr_b16 v[198:199], v226 offset:0x600
	ds_read_b64_tr_b16 v[200:201], v226 offset:0xe00
	ds_read_b64_tr_b16 v[214:215], v226 offset:0x1600
	ds_read_b64_tr_b16 v[216:217], v226 offset:0x1e00
	ds_read_b64_tr_b16 v[218:219], v226 offset:0x2600
	ds_read_b64_tr_b16 v[220:221], v226 offset:0x2e00
	ds_read_b64_tr_b16 v[222:223], v226 offset:0x3600
	ds_read_b64_tr_b16 v[224:225], v226 offset:0x3e00
	s_waitcnt lgkmcnt(8)
	v_mfma_f32_32x32x16_bf16 v[34:49], v[170:173], v[98:101], v[34:49]
	v_mfma_f32_32x32x16_bf16 v[34:49], v[174:177], v[102:105], v[34:49]
	v_mfma_f32_32x32x16_bf16 v[34:49], v[178:181], v[106:109], v[34:49]
	v_mfma_f32_32x32x16_bf16 v[34:49], v[182:185], v[110:113], v[34:49]
	s_waitcnt lgkmcnt(0)
	v_mfma_f32_32x32x16_bf16 v[18:33], v[170:173], v[198:201], v[18:33]
	v_mfma_f32_32x32x16_bf16 v[18:33], v[174:177], v[214:217], v[18:33]
	v_mfma_f32_32x32x16_bf16 v[18:33], v[178:181], v[218:221], v[18:33]
	v_mfma_f32_32x32x16_bf16 v[18:33], v[182:185], v[222:225], v[18:33]
	s_barrier
	s_cmp_gt_u32 s41, 63
	v_lshl_add_u64 v[200:201], v[194:195], 0, s[20:21]
	v_lshl_add_u64 v[198:199], v[196:197], 0, s[20:21]
	s_cbranch_scc1 .LBB0_335
	v_add_co_u32_e32 v98, vcc, 0x20cb8000, v200
	s_nop 1
	v_addc_co_u32_e32 v99, vcc, 0, v201, vcc
	v_add_co_u32_e32 v100, vcc, 0x20cc8000, v200
	s_nop 1
	v_addc_co_u32_e32 v101, vcc, 0, v201, vcc
	global_load_dwordx4 v[146:149], v[98:99], off offset:256
	global_load_dwordx4 v[150:153], v[100:101], off offset:256
	v_add_co_u32_e32 v98, vcc, 0x1c8b8000, v198
	s_nop 1
	v_addc_co_u32_e32 v99, vcc, 0, v199, vcc
	global_load_dwordx4 v[158:161], v[98:99], off offset:256

; #define SBAR() __builtin_amdgcn_sched_barrier(0)
; #define SWRITE(b, S) do { *(bf16x8*)(V_lds + (b) * SHM_V + vst0) = vs##S##0; *(bf16x8*)(V_lds + (b) * SHM_V + vst1) = vs##S##1; \
;     *(bf16x8*)(K_lds + (b) * SHM_K + kst) = ks##S; } while (0)
; #define SWAIT() asm volatile("s_waitcnt vmcnt(3)" ::: "memory")
; __device__ __forceinline__ void attn_stream(const u16* __restrict__ Qb, const u16* __restrict__ Kh, const u16* __restrict__ Vh,
;                                             int seq, char* lds, f32x16 (&o)[4]) {
;     ...
;     SBAR(); __syncthreads(); SBAR();
;     if (j + 3 < NT) { SWAIT(); SWRITE(b0, B); }
;     if (j + 2 < NT) qkt(p0, p1, K_lds + b2 * SHM_K, qr, r32, hi, negm);
;     pv_d0(o, vb0 + b1 * SHM_V, pa0, pa1, pa2, pa3);
.LBB0_341:
	s_lshl_b32 s98, s46, 13
	v_add_u32_e32 v252, s98, v208
	v_add_u32_e32 v253, s98, v209
	v_add_u32_e32 v254, s98, v210
	v_add_u32_e32 v255, s98, v211
	ds_read_b128 v[236:239], v252 offset:49152
	ds_read_b128 v[240:243], v253 offset:49152
	ds_read_b128 v[244:247], v254 offset:49152
	ds_read_b128 v[248:251], v255 offset:49152
	s_barrier
.LBB0_343:
	v_cndmask_b32_e64 v217, 0, 1, s[44:45]
	v_cmp_ne_u32_e64 s[6:7], 1, v217
	s_andn2_b64 vcc, exec, s[44:45]
	s_cbranch_vccnz .LBB0_345
	s_lshl_b32 s44, s46, 13
	s_add_i32 s44, s44, 0
	v_add_u32_e32 v82, s44, v208
	v_add_u32_e32 v83, s44, v209
	v_add_u32_e32 v84, s44, v210
	v_add_u32_e32 v85, s44, v211
	v_lshl_add_u32 v217, s47, 14, v213
	ds_read_b128 v[218:221], v82 offset:53248
	ds_read_b128 v[222:225], v83 offset:53248
	ds_read_b128 v[226:229], v84 offset:53248
	ds_read_b128 v[230:233], v85 offset:53248
	ds_read_b64_tr_b16 v[98:99], v217 offset:0
	ds_read_b64_tr_b16 v[100:101], v217 offset:0x800
	ds_read_b64_tr_b16 v[102:103], v217 offset:0x1000
	ds_read_b64_tr_b16 v[104:105], v217 offset:0x1800
	ds_read_b64_tr_b16 v[106:107], v217 offset:0x2000
	ds_read_b64_tr_b16 v[108:109], v217 offset:0x2800
	ds_read_b64_tr_b16 v[110:111], v217 offset:0x3000
	ds_read_b64_tr_b16 v[112:113], v217 offset:0x3800
	s_waitcnt lgkmcnt(12)
	v_mfma_f32_32x32x16_bf16 v[82:97], v[236:239], v[130:133], v[66:81]
	v_mfma_f32_32x32x16_bf16 v[82:97], v[240:243], v[134:137], v[82:97]
	v_mfma_f32_32x32x16_bf16 v[82:97], v[244:247], v[138:141], v[82:97]
	v_mfma_f32_32x32x16_bf16 v[82:97], v[248:251], v[142:145], v[82:97]
	s_waitcnt lgkmcnt(8)
	s_cmp_gt_u32 s41, 64
	s_cbranch_scc1 .Lattn_odw_1
	s_waitcnt vmcnt(3)
	s_cmp_lt_u32 s41, 64
	s_cbranch_scc1 .Lattn_oddw_1
	s_waitcnt vmcnt(0)
.Lattn_oddw_1:
	s_add_i32 s98, s49, 0
	v_add_u32_e32 v252, s98, v205
	v_lshl_add_u32 v254, s48, 13, v207
	v_add_u32_e32 v253, s98, v206
	ds_write_b128 v252, v[154:157]
	ds_write_b128 v253, v[162:165]
	ds_write_b128 v254, v[166:169] offset:49152
.Lattn_odw_1:
	v_mfma_f32_32x32x16_bf16 v[114:129], v[218:221], v[130:133], v[66:81]
	v_mfma_f32_32x32x16_bf16 v[114:129], v[222:225], v[134:137], v[114:129]
	v_mfma_f32_32x32x16_bf16 v[114:129], v[226:229], v[138:141], v[114:129]
	v_mfma_f32_32x32x16_bf16 v[114:129], v[230:233], v[142:145], v[114:129]
	s_branch .Lattn_pvb2_1

; #define SBAR() __builtin_amdgcn_sched_barrier(0)
; __device__ __forceinline__ void attn_stream(const u16* __restrict__ Qb, const u16* __restrict__ Kh, const u16* __restrict__ Vh,
;                                             int seq, char* lds, f32x16 (&o)[4]) {
;     ...
;     SBAR(); __syncthreads(); SBAR();
;     t3 = b2;
.LBB0_355:
	s_add_i32 s41, s41, 2
	s_lshl_b32 s98, s48, 13
	v_add_u32_e32 v252, s98, v208
	v_add_u32_e32 v253, s98, v209
	v_add_u32_e32 v254, s98, v210
	v_add_u32_e32 v255, s98, v211
	ds_read_b128 v[236:239], v252 offset:49152
	ds_read_b128 v[240:243], v253 offset:49152
	ds_read_b128 v[244:247], v254 offset:49152
	ds_read_b128 v[248:251], v255 offset:49152
	s_barrier
	v_lshl_add_u64 v[194:195], v[194:195], 0, s[12:13]
	v_lshl_add_u64 v[196:197], v[196:197], 0, s[12:13]
	s_and_b64 vcc, exec, s[42:43]
	s_cbranch_vccnz .LBB0_359
	s_mov_b32 s48, s46
	s_branch .LBB0_331

; #define SBAR() __builtin_amdgcn_sched_barrier(0)
; __device__ __forceinline__ int opq(int x) { asm volatile("" : "+v"(x)); return x; }
; __device__ __forceinline__ int v_st(int k, int c) { const int kk = (k & ~0xC) | ((k & 4) << 1) | ((k & 8) >> 1); return ((kk >> 3) * 4 + (c >> 5)) * 512 + ((kk & 7) * 32 + (c & 31)) * 2; }
; __device__ __forceinline__ int v_rd_base(int lane) { return ((lane & 3) << 3) | (((lane >> 2) & 3) << 6) | (((lane >> 4) & 1) << 5) | (((lane >> 5) & 1) << 8); }
; __device__ __forceinline__ void qkt(f32x16& p0, f32x16& p1, const char* Ks, const bf16x8* qr, int r32, int hi, const f32x16& negm) {
;     ...
;   for (int d0 = 0; d0 < 4; ++d0) { const int cb = (d0 * 16 + hi * 8) * 2;
;     ka[d0] = *reinterpret_cast<const bf16x8*>(Ks + KSWZ(r32, cb)); }
; __device__ __forceinline__ void attn_stream(const u16* __restrict__ Qb, const u16* __restrict__ Kh, const u16* __restrict__ Vh,
;                                             int seq, char* lds, f32x16 (&o)[4]) {
;     ...
;   const int tid = opq((int)threadIdx.x), wid = tid >> 6, lane = tid & 63, r32 = lane & 31, hi = lane >> 5;
;   char* V_lds = lds; char* K_lds = lds + 3 * SHM_V;
;   float* wsl = (float*)(lds + 3 * SHM_V + 3 * SHM_K) + wid * 64; float* li_l = wsl; float* al_l = wsl + 32;
;   float m_reg = 0.f, l_reg = 0.f; bf16x8 qr[4]; f32x16 negm = {};
; #pragma unroll
;   for (int d = 0; d < 4; ++d) o[d] = f32x16{};
;   const u16* Qw = Qb + (size_t)(wid * 32 + r32) * LDQ + hi * 8;
; #pragma unroll
;   for (int d0 = 0; d0 < 4; ++d0) qr[d0] = *reinterpret_cast<const bf16x8*>(Qw + d0 * 16);
;   const int sr = tid >> 4, sc = (tid & 15) * 8, vst0 = v_st(sr, sc), vst1 = v_st(32 + sr, sc);
;   const int kr = tid >> 3, kc = (tid & 7) * 8, kst = KSWZ(kr, kc * 2);
;   const int vb0 = (int)(uintptr_t)(__attribute__((address_space(3))) char*)V_lds + v_rd_base(lane);
;   bf16x8 vsA0, vsA1, ksA, vsB0, vsB1, ksB;
;     ...
;   f32x16 p0, p1; float al; bf16x8 pa0, pa1, pa2, pa3; const int NT = seq / 64;
;     ...
;   const bool late = wid >= 4;
;   __syncthreads();
;   SLOAD(A, 0); SLOAD(B, 64); asm volatile("s_waitcnt vmcnt(0)" ::: "memory"); SWRITE(0, A); SWRITE(1, B);
;   SLOAD(A, 128); SLOAD(B, 192);
;   __syncthreads();
;   qkt(p0, p1, K_lds, qr, r32, hi, negm); SOFTMAX(true); SBAR();
;   if (late) __syncthreads();
;   int t3 = 0;
.LBB0_370:
	s_or_b64 exec, exec, s[4:5]
	v_lshlrev_b32_e32 v19, 4, v43
	v_lshlrev_b32_e32 v18, 3, v43
	v_and_b32_e32 v19, 0xc0, v19
	v_lshlrev_b32_e32 v20, 1, v43
	v_and_or_b32 v19, v18, 24, v19
	v_and_b32_e32 v20, 32, v20
	v_and_b32_e32 v18, 0x100, v18
	v_or3_b32 v18, v19, v20, v18
	v_and_b32_e32 v20, 15, v40
	v_add_u32_e32 v213, 0, v18
	v_lshl_add_u64 v[18:19], s[56:57], 0, v[34:35]
	v_lshlrev_b32_e32 v20, 4, v20
	v_mov_b32_e32 v21, v191
	v_lshl_add_u64 v[18:19], v[18:19], 0, v[20:21]
	v_and_b32_e32 v20, 7, v40
	v_lshl_add_u64 v[194:195], s[26:27], 0, v[18:19]
	v_lshl_add_u64 v[18:19], s[56:57], 0, v[36:37]
	v_lshlrev_b32_e32 v20, 4, v20
	v_lshl_add_u64 v[18:19], v[18:19], 0, v[20:21]
	v_cmp_gt_u32_e64 s[4:5], 32, v43
	v_lshl_add_u32 v212, v41, 2, v204
	v_lshl_add_u64 v[196:197], s[26:27], 0, v[18:19]
	v_mov_b64_e32 v[64:65], v[16:17]
	v_mov_b64_e32 v[48:49], v[16:17]
	v_mov_b64_e32 v[32:33], v[16:17]
	s_mov_b32 s38, 0
	v_mov_b64_e32 v[62:63], v[14:15]
	v_mov_b64_e32 v[60:61], v[12:13]
	v_mov_b64_e32 v[58:59], v[10:11]
	v_mov_b64_e32 v[56:57], v[8:9]
	v_mov_b64_e32 v[54:55], v[6:7]
	v_mov_b64_e32 v[52:53], v[4:5]
	v_mov_b64_e32 v[50:51], v[2:3]
	v_mov_b64_e32 v[46:47], v[14:15]
	v_mov_b64_e32 v[44:45], v[12:13]
	v_mov_b64_e32 v[42:43], v[10:11]
	v_mov_b64_e32 v[40:41], v[8:9]
	v_mov_b64_e32 v[38:39], v[6:7]
	v_mov_b64_e32 v[36:37], v[4:5]
	v_mov_b64_e32 v[34:35], v[2:3]
	v_mov_b64_e32 v[30:31], v[14:15]
	v_mov_b64_e32 v[28:29], v[12:13]
	v_mov_b64_e32 v[26:27], v[10:11]
	v_mov_b64_e32 v[24:25], v[8:9]
	v_mov_b64_e32 v[22:23], v[6:7]
	v_mov_b64_e32 v[20:21], v[4:5]
	v_mov_b64_e32 v[18:19], v[2:3]
	s_mov_b32 s42, 0
	v_mov_b32_e32 v67, v66
	v_mov_b32_e32 v68, v66
	v_mov_b32_e32 v69, v66
	v_mov_b32_e32 v70, v66
	v_mov_b32_e32 v71, v66
	v_mov_b32_e32 v72, v66
	v_mov_b32_e32 v73, v66
	v_mov_b32_e32 v74, v66
	v_mov_b32_e32 v75, v66
	v_mov_b32_e32 v76, v66
	v_mov_b32_e32 v77, v66
	v_mov_b32_e32 v78, v66
	v_mov_b32_e32 v79, v66
	v_mov_b32_e32 v80, v66
	v_mov_b32_e32 v81, v66
	s_mov_b32 s99, 1
	s_lshl_b32 s98, s99, 13
	v_add_u32_e32 v252, s98, v208
	v_add_u32_e32 v253, s98, v209
	v_add_u32_e32 v254, s98, v210
	v_add_u32_e32 v255, s98, v211
	ds_read_b128 v[236:239], v252 offset:49152
	ds_read_b128 v[240:243], v253 offset:49152
	ds_read_b128 v[244:247], v254 offset:49152
	ds_read_b128 v[248:251], v255 offset:49152

; #define SBAR() __builtin_amdgcn_sched_barrier(0)
; __device__ __forceinline__ void qkt(f32x16& p0, f32x16& p1, const char* Ks, const bf16x8* qr, int r32, int hi, const f32x16& negm) {
;   bf16x8 ka[4], kb[4];
; #pragma unroll
;   for (int d0 = 0; d0 < 4; ++d0) { const int cb = (d0 * 16 + hi * 8) * 2;
;     ka[d0] = *reinterpret_cast<const bf16x8*>(Ks + KSWZ(r32, cb)); }
; #pragma unroll
;   for (int d0 = 0; d0 < 4; ++d0) { const int cb = (d0 * 16 + hi * 8) * 2;
;     kb[d0] = *reinterpret_cast<const bf16x8*>(Ks + KSWZ(32 + r32, cb)); }
;   asm volatile("s_waitcnt lgkmcnt(0)" ::: "memory");
; #pragma unroll
;   for (int d0 = 0; d0 < 4; ++d0) { asm volatile("" : "+v"(ka[d0])); asm volatile("" : "+v"(kb[d0])); }
;   SBAR();
;   p0 = __builtin_amdgcn_mfma_f32_32x32x16_bf16(ka[0], qr[0], negm, 0, 0, 0);
;   p0 = __builtin_amdgcn_mfma_f32_32x32x16_bf16(ka[1], qr[1], p0, 0, 0, 0);
;   p0 = __builtin_amdgcn_mfma_f32_32x32x16_bf16(ka[2], qr[2], p0, 0, 0, 0);
;   p0 = __builtin_amdgcn_mfma_f32_32x32x16_bf16(ka[3], qr[3], p0, 0, 0, 0);
;   p1 = __builtin_amdgcn_mfma_f32_32x32x16_bf16(kb[0], qr[0], negm, 0, 0, 0);
;   p1 = __builtin_amdgcn_mfma_f32_32x32x16_bf16(kb[1], qr[1], p1, 0, 0, 0);
;   p1 = __builtin_amdgcn_mfma_f32_32x32x16_bf16(kb[2], qr[2], p1, 0, 0, 0);
;   p1 = __builtin_amdgcn_mfma_f32_32x32x16_bf16(kb[3], qr[3], p1, 0, 0, 0);
;   SBAR();
; }
; __device__ __forceinline__ int v_st(int k, int c) { const int kk = (k & ~0xC) | ((k & 4) << 1) | ((k & 8) >> 1); return ((kk >> 3) * 4 + (c >> 5)) * 512 + ((kk & 7) * 32 + (c & 31)) * 2; }
; __device__ __forceinline__ int v_rd_base(int lane) { return ((lane & 3) << 3) | (((lane >> 2) & 3) << 6) | (((lane >> 4) & 1) << 5) | (((lane >> 5) & 1) << 8); }
; template <int OFF> __device__ __forceinline__ s16x4 tr_read(int vb) {
;   s16x4 r; asm volatile("ds_read_b64_tr_b16 %0, %1 offset:%2" : "=&v"(r) : "v"(vb), "i"(OFF) : "memory"); return r;
; }
; template <int D0> __device__ __forceinline__ void pv_rd(s16x4 (&v)[8], int vb) {
;   v[0] = tr_read<v_rd_off(D0, 0, 0)>(vb); v[1] = tr_read<v_rd_off(D0, 0, 1)>(vb); v[2] = tr_read<v_rd_off(D0, 1, 0)>(vb); v[3] = tr_read<v_rd_off(D0, 1, 1)>(vb);
;   v[4] = tr_read<v_rd_off(D0, 2, 0)>(vb); v[5] = tr_read<v_rd_off(D0, 2, 1)>(vb); v[6] = tr_read<v_rd_off(D0, 3, 0)>(vb); v[7] = tr_read<v_rd_off(D0, 3, 1)>(vb);
; }
.LBB0_373:
	s_lshl_b32 s6, s41, 13
	s_add_i32 s6, s6, 0
	v_add_u32_e32 v82, s6, v208
	v_add_u32_e32 v83, s6, v209
	v_add_u32_e32 v84, s6, v210
	v_add_u32_e32 v85, s6, v211
	s_lshl_b32 s43, s42, 14
	v_add_u32_e32 v226, s43, v213
	ds_read_b128 v[218:221], v82 offset:53248
	ds_read_b128 v[222:225], v83 offset:53248
	ds_read_b128 v[198:201], v84 offset:53248
	ds_read_b128 v[214:217], v85 offset:53248
	ds_read_b64_tr_b16 v[98:99], v226 offset:0
	ds_read_b64_tr_b16 v[100:101], v226 offset:0x800
	ds_read_b64_tr_b16 v[102:103], v226 offset:0x1000
	ds_read_b64_tr_b16 v[104:105], v226 offset:0x1800
	ds_read_b64_tr_b16 v[106:107], v226 offset:0x2000
	ds_read_b64_tr_b16 v[108:109], v226 offset:0x2800
	ds_read_b64_tr_b16 v[110:111], v226 offset:0x3000
	ds_read_b64_tr_b16 v[112:113], v226 offset:0x3800
	s_waitcnt lgkmcnt(12)
	v_mfma_f32_32x32x16_bf16 v[82:97], v[236:239], v[130:133], v[66:81]
	v_mfma_f32_32x32x16_bf16 v[82:97], v[240:243], v[134:137], v[82:97]
	v_mfma_f32_32x32x16_bf16 v[82:97], v[244:247], v[138:141], v[82:97]
	v_mfma_f32_32x32x16_bf16 v[82:97], v[248:251], v[142:145], v[82:97]
	s_waitcnt lgkmcnt(8)
	s_and_b64 vcc, exec, s[30:31]
	s_cbranch_vccnz .Lattn_evw_2
	s_lshl_b32 s98, s39, 14
	s_waitcnt vmcnt(3)
	v_add_u32_e32 v252, s98, v205
	v_lshl_add_u32 v254, s39, 13, v207
	v_add_u32_e32 v253, s98, v206
	ds_write_b128 v252, v[146:149]
	ds_write_b128 v253, v[150:153]
	ds_write_b128 v254, v[158:161] offset:49152
.Lattn_evw_2:
	v_mfma_f32_32x32x16_bf16 v[114:129], v[218:221], v[130:133], v[66:81]
	v_mfma_f32_32x32x16_bf16 v[114:129], v[222:225], v[134:137], v[114:129]
	v_mfma_f32_32x32x16_bf16 v[114:129], v[198:201], v[138:141], v[114:129]
	v_mfma_f32_32x32x16_bf16 v[114:129], v[214:217], v[142:145], v[114:129]
	ds_read_b64_tr_b16 v[198:199], v226 offset:0x200
	ds_read_b64_tr_b16 v[200:201], v226 offset:0xa00
	ds_read_b64_tr_b16 v[214:215], v226 offset:0x1200
	ds_read_b64_tr_b16 v[216:217], v226 offset:0x1a00
	ds_read_b64_tr_b16 v[218:219], v226 offset:0x2200
	ds_read_b64_tr_b16 v[220:221], v226 offset:0x2a00
	ds_read_b64_tr_b16 v[222:223], v226 offset:0x3200
	ds_read_b64_tr_b16 v[224:225], v226 offset:0x3a00
	s_waitcnt lgkmcnt(8)
	s_nop 0
	v_mfma_f32_32x32x16_bf16 v[2:17], v[170:173], v[98:101], v[2:17]
	v_mfma_f32_32x32x16_bf16 v[2:17], v[174:177], v[102:105], v[2:17]
	v_mfma_f32_32x32x16_bf16 v[2:17], v[178:181], v[106:109], v[2:17]
	v_mfma_f32_32x32x16_bf16 v[2:17], v[182:185], v[110:113], v[2:17]
	ds_read_b64_tr_b16 v[98:99], v226 offset:0x400
	ds_read_b64_tr_b16 v[100:101], v226 offset:0xc00
	ds_read_b64_tr_b16 v[102:103], v226 offset:0x1400
	ds_read_b64_tr_b16 v[104:105], v226 offset:0x1c00
	ds_read_b64_tr_b16 v[106:107], v226 offset:0x2400
	ds_read_b64_tr_b16 v[108:109], v226 offset:0x2c00
	ds_read_b64_tr_b16 v[110:111], v226 offset:0x3400
	ds_read_b64_tr_b16 v[112:113], v226 offset:0x3c00
	s_waitcnt lgkmcnt(8)
	v_mfma_f32_32x32x16_bf16 v[50:65], v[170:173], v[198:201], v[50:65]
	v_mfma_f32_32x32x16_bf16 v[50:65], v[174:177], v[214:217], v[50:65]
	v_mfma_f32_32x32x16_bf16 v[50:65], v[178:181], v[218:221], v[50:65]
	v_mfma_f32_32x32x16_bf16 v[50:65], v[182:185], v[222:225], v[50:65]
	ds_read_b64_tr_b16 v[198:199], v226 offset:0x600
	ds_read_b64_tr_b16 v[200:201], v226 offset:0xe00
	ds_read_b64_tr_b16 v[214:215], v226 offset:0x1600
	ds_read_b64_tr_b16 v[216:217], v226 offset:0x1e00
	ds_read_b64_tr_b16 v[218:219], v226 offset:0x2600
	ds_read_b64_tr_b16 v[220:221], v226 offset:0x2e00
	ds_read_b64_tr_b16 v[222:223], v226 offset:0x3600
	ds_read_b64_tr_b16 v[224:225], v226 offset:0x3e00
	s_waitcnt lgkmcnt(8)
	v_mfma_f32_32x32x16_bf16 v[34:49], v[170:173], v[98:101], v[34:49]
	v_mfma_f32_32x32x16_bf16 v[34:49], v[174:177], v[102:105], v[34:49]
	v_mfma_f32_32x32x16_bf16 v[34:49], v[178:181], v[106:109], v[34:49]
	v_mfma_f32_32x32x16_bf16 v[34:49], v[182:185], v[110:113], v[34:49]
	s_waitcnt lgkmcnt(0)
	v_mfma_f32_32x32x16_bf16 v[18:33], v[170:173], v[198:201], v[18:33]
	v_mfma_f32_32x32x16_bf16 v[18:33], v[174:177], v[214:217], v[18:33]
	v_mfma_f32_32x32x16_bf16 v[18:33], v[178:181], v[218:221], v[18:33]
	v_mfma_f32_32x32x16_bf16 v[18:33], v[182:185], v[222:225], v[18:33]
	s_barrier
	s_cmp_gt_u32 s38, 63
	v_lshl_add_u64 v[200:201], v[194:195], 0, s[20:21]
	v_lshl_add_u64 v[198:199], v[196:197], 0, s[20:21]
	s_cbranch_scc1 .LBB0_375
	v_add_co_u32_e32 v98, vcc, 0x20cb8000, v200
	s_nop 1
	v_addc_co_u32_e32 v99, vcc, 0, v201, vcc
	v_add_co_u32_e32 v100, vcc, 0x20cc8000, v200
	s_nop 1
	v_addc_co_u32_e32 v101, vcc, 0, v201, vcc
	global_load_dwordx4 v[146:149], v[98:99], off offset:256
	global_load_dwordx4 v[150:153], v[100:101], off offset:256
	v_add_co_u32_e32 v98, vcc, 0x1c8b8000, v198
	s_nop 1
	v_addc_co_u32_e32 v99, vcc, 0, v199, vcc
	global_load_dwordx4 v[158:161], v[98:99], off offset:384

; #define SBAR() __builtin_amdgcn_sched_barrier(0)
; #define SWRITE(b, S) do { *(bf16x8*)(V_lds + (b) * SHM_V + vst0) = vs##S##0; *(bf16x8*)(V_lds + (b) * SHM_V + vst1) = vs##S##1; \
;     *(bf16x8*)(K_lds + (b) * SHM_K + kst) = ks##S; } while (0)
; #define SWAIT() asm volatile("s_waitcnt vmcnt(3)" ::: "memory")
; __device__ __forceinline__ void attn_stream(const u16* __restrict__ Qb, const u16* __restrict__ Kh, const u16* __restrict__ Vh,
;                                             int seq, char* lds, f32x16 (&o)[4]) {
;     ...
;     SBAR(); __syncthreads(); SBAR();
;     if (j + 3 < NT) { SWAIT(); SWRITE(b0, B); }
;     if (j + 2 < NT) qkt(p0, p1, K_lds + b2 * SHM_K, qr, r32, hi, negm);
;     pv_d0(o, vb0 + b1 * SHM_V, pa0, pa1, pa2, pa3);
.LBB0_381:
	s_lshl_b32 s98, s39, 13
	v_add_u32_e32 v252, s98, v208
	v_add_u32_e32 v253, s98, v209
	v_add_u32_e32 v254, s98, v210
	v_add_u32_e32 v255, s98, v211
	ds_read_b128 v[236:239], v252 offset:49152
	ds_read_b128 v[240:243], v253 offset:49152
	ds_read_b128 v[244:247], v254 offset:49152
	ds_read_b128 v[248:251], v255 offset:49152
	s_barrier
.LBB0_383:
	v_cndmask_b32_e64 v217, 0, 1, s[34:35]
	v_cmp_ne_u32_e64 s[6:7], 1, v217
	s_andn2_b64 vcc, exec, s[34:35]
	s_cbranch_vccnz .LBB0_385
	s_lshl_b32 s34, s39, 13
	s_add_i32 s34, s34, 0
	v_add_u32_e32 v82, s34, v208
	v_add_u32_e32 v83, s34, v209
	v_add_u32_e32 v84, s34, v210
	v_add_u32_e32 v85, s34, v211
	v_lshl_add_u32 v217, s41, 14, v213
	ds_read_b128 v[218:221], v82 offset:53248
	ds_read_b128 v[222:225], v83 offset:53248
	ds_read_b128 v[226:229], v84 offset:53248
	ds_read_b128 v[230:233], v85 offset:53248
	ds_read_b64_tr_b16 v[98:99], v217 offset:0
	ds_read_b64_tr_b16 v[100:101], v217 offset:0x800
	ds_read_b64_tr_b16 v[102:103], v217 offset:0x1000
	ds_read_b64_tr_b16 v[104:105], v217 offset:0x1800
	ds_read_b64_tr_b16 v[106:107], v217 offset:0x2000
	ds_read_b64_tr_b16 v[108:109], v217 offset:0x2800
	ds_read_b64_tr_b16 v[110:111], v217 offset:0x3000
	ds_read_b64_tr_b16 v[112:113], v217 offset:0x3800
	s_waitcnt lgkmcnt(12)
	v_mfma_f32_32x32x16_bf16 v[82:97], v[236:239], v[130:133], v[66:81]
	v_mfma_f32_32x32x16_bf16 v[82:97], v[240:243], v[134:137], v[82:97]
	v_mfma_f32_32x32x16_bf16 v[82:97], v[244:247], v[138:141], v[82:97]
	v_mfma_f32_32x32x16_bf16 v[82:97], v[248:251], v[142:145], v[82:97]
	s_waitcnt lgkmcnt(8)
	s_cmp_gt_u32 s38, 64
	s_cbranch_scc1 .Lattn_odw_2
	s_waitcnt vmcnt(3)
	s_cmp_lt_u32 s38, 64
	s_cbranch_scc1 .Lattn_oddw_2
	s_waitcnt vmcnt(0)
.Lattn_oddw_2:
	s_add_i32 s98, s43, 0
	v_add_u32_e32 v252, s98, v205
	v_lshl_add_u32 v254, s42, 13, v207
	v_add_u32_e32 v253, s98, v206
	ds_write_b128 v252, v[154:157]
	ds_write_b128 v253, v[162:165]
	ds_write_b128 v254, v[166:169] offset:49152

; #define SBAR() __builtin_amdgcn_sched_barrier(0)
; __device__ __forceinline__ void attn_stream(const u16* __restrict__ Qb, const u16* __restrict__ Kh, const u16* __restrict__ Vh,
;                                             int seq, char* lds, f32x16 (&o)[4]) {
;     ...
;     SBAR(); __syncthreads(); SBAR();
;     t3 = b2;
.LBB0_395:
	s_add_i32 s38, s38, 2
	s_lshl_b32 s98, s42, 13
	v_add_u32_e32 v252, s98, v208
	v_add_u32_e32 v253, s98, v209
	v_add_u32_e32 v254, s98, v210
	v_add_u32_e32 v255, s98, v211
	ds_read_b128 v[236:239], v252 offset:49152
	ds_read_b128 v[240:243], v253 offset:49152
	ds_read_b128 v[244:247], v254 offset:49152
	ds_read_b128 v[248:251], v255 offset:49152
	s_barrier
	v_lshl_add_u64 v[194:195], v[194:195], 0, s[12:13]
	v_lshl_add_u64 v[196:197], v[196:197], 0, s[12:13]
	s_and_b64 vcc, exec, s[30:31]
	s_cbranch_vccnz .LBB0_399
	s_mov_b32 s42, s39
	s_branch .LBB0_371

; __global__ __launch_bounds__(NTHR, 2) void mega(Params p) {
	.amdhsa_kernel _Z4mega6Params
		.amdhsa_group_segment_fixed_size 0
		.amdhsa_private_segment_fixed_size 0
		.amdhsa_kernarg_size 392
		.amdhsa_user_sgpr_count 2
		.amdhsa_user_sgpr_dispatch_ptr 0
		.amdhsa_user_sgpr_queue_ptr 0
		.amdhsa_user_sgpr_kernarg_segment_ptr 1
		.amdhsa_user_sgpr_dispatch_id 0
		.amdhsa_user_sgpr_kernarg_preload_length 0
		.amdhsa_user_sgpr_kernarg_preload_offset 0
		.amdhsa_user_sgpr_private_segment_size 0
		.amdhsa_uses_dynamic_stack 0
		.amdhsa_enable_private_segment 0
		.amdhsa_system_sgpr_workgroup_id_x 1
		.amdhsa_system_sgpr_workgroup_id_y 0
		.amdhsa_system_sgpr_workgroup_id_z 0
		.amdhsa_system_sgpr_workgroup_info 0
		.amdhsa_system_vgpr_workitem_id 2
		.amdhsa_next_free_vgpr 256
		.amdhsa_next_free_sgpr 100
		.amdhsa_accum_offset 256
		.amdhsa_reserve_vcc 1
		.amdhsa_float_round_mode_32 0
		.amdhsa_float_round_mode_16_64 0
		.amdhsa_float_denorm_mode_32 3
		.amdhsa_float_denorm_mode_16_64 3
		.amdhsa_dx10_clamp 1
		.amdhsa_ieee_mode 1
		.amdhsa_fp16_overflow 0
		.amdhsa_tg_split 0
		.amdhsa_exception_fp_ieee_invalid_op 0
		.amdhsa_exception_fp_denorm_src 0
		.amdhsa_exception_fp_ieee_div_zero 0
		.amdhsa_exception_fp_ieee_overflow 0
		.amdhsa_exception_fp_ieee_underflow 0
		.amdhsa_exception_fp_ieee_inexact 0
		.amdhsa_exception_int_div_zero 0
	.end_amdhsa_kernel

; __global__ __launch_bounds__(NTHR, 2) void mega(Params p) {
amdhsa.kernels:
  - .agpr_count:     0
    .args:
      - .offset:         0
        .size:           136
        .value_kind:     by_value
      - .offset:         136
        .size:           4
        .value_kind:     hidden_block_count_x
      - .offset:         140
        .size:           4
        .value_kind:     hidden_block_count_y
      - .offset:         144
        .size:           4
        .value_kind:     hidden_block_count_z
      - .offset:         148
        .size:           2
        .value_kind:     hidden_group_size_x
      - .offset:         150
        .size:           2
        .value_kind:     hidden_group_size_y
      - .offset:         152
        .size:           2
        .value_kind:     hidden_group_size_z
      - .offset:         154
        .size:           2
        .value_kind:     hidden_remainder_x
      - .offset:         156
        .size:           2
        .value_kind:     hidden_remainder_y
      - .offset:         158
        .size:           2
        .value_kind:     hidden_remainder_z
      - .offset:         176
        .size:           8
        .value_kind:     hidden_global_offset_x
      - .offset:         184
        .size:           8
        .value_kind:     hidden_global_offset_y
      - .offset:         192
        .size:           8
        .value_kind:     hidden_global_offset_z
      - .offset:         200
        .size:           2
        .value_kind:     hidden_grid_dims
      - .offset:         224
        .size:           8
        .value_kind:     hidden_multigrid_sync_arg
      - .offset:         256
        .size:           4
        .value_kind:     hidden_dynamic_lds_size
    .group_segment_fixed_size: 0
    .kernarg_segment_align: 8
    .kernarg_segment_size: 392
    .language:       OpenCL C
    .language_version:
      - 2
      - 0
    .max_flat_workgroup_size: 512
    .name:           _Z4mega6Params
    .private_segment_fixed_size: 0
    .sgpr_count:     106
    .sgpr_spill_count: 0
    .symbol:         _Z4mega6Params.kd
    .uniform_work_group_size: 1
    .uses_dynamic_stack: false
    .vgpr_count:     256
    .vgpr_spill_count: 0
    .wavefront_size: 64
